# P0 weight-transpose items: 8 row+gain loads batched (was serialized); band-attn counted waits; P11 ssq loads batched; scan n-lanes reuse loaded gates
# speedup vs baseline: 1.0137x; 1.0044x over previous
.LBB0_41:
	s_andn2_b64 vcc, exec, s[0:1]
	s_cbranch_vccnz .LBB0_59
	s_add_i32 s0, s47, 0xee80
	s_and_b32 s1, s0, 0xffff
	s_mul_i32 s1, s1, 0xba2f
	s_lshr_b32 s1, s1, 23
	s_mul_i32 s4, s1, 0xb0
	s_sub_i32 s0, s0, s4
	s_and_b32 s28, s0, 0xffff
	s_lshl_b32 s5, s1, 6
	s_bfe_i32 s0, s0, 0x10002
	s_lshl_b32 s1, s28, 4
	s_lshl_b32 s4, s28, 5
	s_and_b32 s0, s0, 0xb00
	s_and_b32 s1, s1, 0xf80
	s_add_i32 s0, s0, s1
	s_and_b32 s1, s4, 0x60
	s_or_b32 s0, s0, s1
	v_or_b32_e32 v0, s0, v41
	s_mov_b64 s[0:1], s[50:51]
	v_readlane_b32 s48, v250, 5
	v_lshlrev_b32_e32 v14, 2, v0
	v_readlane_b32 s49, v250, 6
	v_readlane_b32 s50, v250, 7
	v_readlane_b32 s51, v250, 8
	v_lshl_add_u64 v[8:9], s[48:49], 0, v[14:15]
	v_or_b32_e32 v4, s5, v12
	s_mov_b64 s[50:51], s[0:1]
	v_mad_u64_u32 v[0:1], s[0:1], v4, s44, v[8:9]
	global_load_dwordx4 v[108:111], v[0:1], off
	v_readlane_b32 s52, v250, 9
	v_readlane_b32 s53, v250, 10
	v_readlane_b32 s54, v250, 11
	v_readlane_b32 s55, v250, 12
	v_or_b32_e32 v174, s5, v43
	v_mad_u64_u32 v[174:175], s[30:31], v174, s44, v[8:9]
	global_load_dwordx4 v[112:115], v[174:175], off
	v_or_b32_e32 v176, s5, v45
	v_mad_u64_u32 v[176:177], s[30:31], v176, s44, v[8:9]
	global_load_dwordx4 v[116:119], v[176:177], off
	v_or_b32_e32 v178, s5, v47
	v_mad_u64_u32 v[178:179], s[30:31], v178, s44, v[8:9]
	global_load_dwordx4 v[120:123], v[178:179], off
	v_or_b32_e32 v180, s5, v48
	v_mad_u64_u32 v[180:181], s[30:31], v180, s44, v[8:9]
	global_load_dwordx4 v[124:127], v[180:181], off
	v_or_b32_e32 v182, s5, v49
	v_mad_u64_u32 v[182:183], s[30:31], v182, s44, v[8:9]
	global_load_dwordx4 v[128:131], v[182:183], off
	v_or_b32_e32 v184, s5, v50
	v_mad_u64_u32 v[184:185], s[30:31], v184, s44, v[8:9]
	global_load_dwordx4 v[132:135], v[184:185], off
	v_or_b32_e32 v186, s5, v51
	v_mad_u64_u32 v[186:187], s[30:31], v186, s44, v[8:9]
	global_load_dwordx4 v[136:139], v[186:187], off
	s_andn2_b64 vcc, exec, s[50:51]
	s_cbranch_vccnz .Ltr_d_nogain
	v_add_lshl_u32 v10, v12, s5, 2
	global_load_dword v140, v10, s[62:63]
	global_load_dword v142, v10, s[62:63] offset:32
	global_load_dword v144, v10, s[62:63] offset:64
	global_load_dword v146, v10, s[62:63] offset:96
	global_load_dword v148, v10, s[62:63] offset:128
	global_load_dword v150, v10, s[62:63] offset:160
	global_load_dword v152, v10, s[62:63] offset:192
	global_load_dword v154, v10, s[62:63] offset:224
	s_waitcnt vmcnt(0)
	v_pk_mul_f32 v[108:109], v[108:109], v[140:141] op_sel_hi:[1,0]
	v_pk_mul_f32 v[110:111], v[110:111], v[140:141] op_sel_hi:[1,0]
	v_pk_mul_f32 v[112:113], v[112:113], v[142:143] op_sel_hi:[1,0]
	v_pk_mul_f32 v[114:115], v[114:115], v[142:143] op_sel_hi:[1,0]
	v_pk_mul_f32 v[116:117], v[116:117], v[144:145] op_sel_hi:[1,0]
	v_pk_mul_f32 v[118:119], v[118:119], v[144:145] op_sel_hi:[1,0]
	v_pk_mul_f32 v[120:121], v[120:121], v[146:147] op_sel_hi:[1,0]
	v_pk_mul_f32 v[122:123], v[122:123], v[146:147] op_sel_hi:[1,0]
	v_pk_mul_f32 v[124:125], v[124:125], v[148:149] op_sel_hi:[1,0]
	v_pk_mul_f32 v[126:127], v[126:127], v[148:149] op_sel_hi:[1,0]
	v_pk_mul_f32 v[128:129], v[128:129], v[150:151] op_sel_hi:[1,0]
	v_pk_mul_f32 v[130:131], v[130:131], v[150:151] op_sel_hi:[1,0]
	v_pk_mul_f32 v[132:133], v[132:133], v[152:153] op_sel_hi:[1,0]
	v_pk_mul_f32 v[134:135], v[134:135], v[152:153] op_sel_hi:[1,0]
	v_pk_mul_f32 v[136:137], v[136:137], v[154:155] op_sel_hi:[1,0]
	v_pk_mul_f32 v[138:139], v[138:139], v[154:155] op_sel_hi:[1,0]
.Ltr_d_nogain:
	s_waitcnt vmcnt(0)
	ds_write2_b32 v53, v108, v109 offset1:1
	ds_write2_b32 v53, v110, v111 offset0:2 offset1:3
	v_add_u32_e32 v188, v42, v44
	ds_write2_b32 v188, v112, v113 offset1:1
	ds_write2_b32 v188, v114, v115 offset0:2 offset1:3
	v_add_u32_e32 v190, v42, v46
	ds_write2_b32 v190, v116, v117 offset1:1
	ds_write2_b32 v190, v118, v119 offset0:2 offset1:3
	v_add_u32_e32 v188, 0x420, v190
	ds_write2_b32 v188, v120, v121 offset1:1
	v_add_u32_e32 v189, 0x428, v190
	ds_write2_b32 v189, v122, v123 offset1:1
	v_add_u32_e32 v188, 0x840, v190
	ds_write2_b32 v188, v124, v125 offset1:1
	v_add_u32_e32 v189, 0x848, v190
	ds_write2_b32 v189, v126, v127 offset1:1
	v_add_u32_e32 v188, 0xc60, v190
	ds_write2_b32 v188, v128, v129 offset1:1
	v_add_u32_e32 v189, 0xc68, v190
	ds_write2_b32 v189, v130, v131 offset1:1
	v_add_u32_e32 v188, 0x1080, v190
	ds_write2_b32 v188, v132, v133 offset1:1
	v_add_u32_e32 v189, 0x1088, v190
	ds_write2_b32 v189, v134, v135 offset1:1
	v_add_u32_e32 v188, 0x14a0, v190
	ds_write2_b32 v188, v136, v137 offset1:1
	v_add_u32_e32 v189, 0x14a8, v190
	ds_write2_b32 v189, v138, v139 offset1:1
	s_waitcnt lgkmcnt(0)
	ds_read2_b32 v[4:5], v52 offset0:33 offset1:41
	ds_read2_b32 v[6:7], v52 offset1:8
	ds_read2_b32 v[8:9], v52 offset0:66 offset1:74
	ds_read2_b32 v[10:11], v52 offset0:99 offset1:107
	ds_read2_b32 v[38:39], v52 offset0:132 offset1:140
	ds_read2_b32 v[66:67], v52 offset0:165 offset1:173
	ds_read2_b32 v[68:69], v52 offset0:198 offset1:206
	ds_read2_b32 v[70:71], v52 offset0:231 offset1:239
	s_lshl_b32 s28, s5, 1
	s_waitcnt lgkmcnt(6)
	v_cvt_pk_bf16_f32 v0, v6, v4
	v_or_b32_e32 v4, s4, v12
	v_lshl_add_u64 v[72:73], v[22:23], 0, s[28:29]
	v_lshlrev_b32_e32 v14, 11, v4
	s_waitcnt lgkmcnt(4)
	v_cvt_pk_bf16_f32 v1, v8, v10
	s_waitcnt lgkmcnt(2)
	v_cvt_pk_bf16_f32 v2, v38, v66
	s_waitcnt lgkmcnt(0)
	v_cvt_pk_bf16_f32 v3, v68, v70
	v_lshl_add_u64 v[74:75], v[72:73], 0, v[14:15]
	global_store_dwordx4 v[74:75], v[0:3], off
	v_or_b32_e32 v4, s4, v43
	v_lshlrev_b32_e32 v14, 11, v4
	v_cvt_pk_bf16_f32 v0, v7, v5
	v_cvt_pk_bf16_f32 v1, v9, v11
	v_cvt_pk_bf16_f32 v2, v39, v67
	v_cvt_pk_bf16_f32 v3, v69, v71
	ds_read2_b32 v[6:7], v52 offset0:49 offset1:57
	ds_read2_b32 v[8:9], v52 offset0:16 offset1:24
	ds_read2_b32 v[10:11], v52 offset0:82 offset1:90
	ds_read2_b32 v[38:39], v52 offset0:115 offset1:123
	ds_read2_b32 v[66:67], v52 offset0:148 offset1:156
	ds_read2_b32 v[68:69], v52 offset0:181 offset1:189
	ds_read2_b32 v[70:71], v52 offset0:214 offset1:222
	ds_read2_b32 v[74:75], v52 offset0:247 offset1:255
	v_lshl_add_u64 v[4:5], v[72:73], 0, v[14:15]
	global_store_dwordx4 v[4:5], v[0:3], off
	v_or_b32_e32 v4, s4, v45
	v_lshlrev_b32_e32 v14, 11, v4
	s_waitcnt lgkmcnt(6)
	v_cvt_pk_bf16_f32 v0, v8, v6
	s_waitcnt lgkmcnt(4)
	v_cvt_pk_bf16_f32 v1, v10, v38
	s_waitcnt lgkmcnt(2)
	v_cvt_pk_bf16_f32 v2, v66, v68
	s_waitcnt lgkmcnt(0)
	v_cvt_pk_bf16_f32 v3, v70, v74
	v_lshl_add_u64 v[4:5], v[72:73], 0, v[14:15]
	global_store_dwordx4 v[4:5], v[0:3], off
	v_or_b32_e32 v4, s4, v47
	v_lshlrev_b32_e32 v14, 11, v4
	v_cvt_pk_bf16_f32 v0, v9, v7
	v_cvt_pk_bf16_f32 v1, v11, v39
	v_cvt_pk_bf16_f32 v2, v67, v69
	v_cvt_pk_bf16_f32 v3, v71, v75
	v_lshl_add_u64 v[4:5], v[72:73], 0, v[14:15]
	global_store_dwordx4 v[4:5], v[0:3], off
	s_waitcnt lgkmcnt(0)
	s_mov_b32 s30, s82

.LBB0_69:
	s_andn2_b64 vcc, exec, s[0:1]
	s_cbranch_vccnz .LBB0_88
	s_add_i32 s0, s47, 0xf580
	s_and_b32 s1, s0, 0xffff
	s_mul_i32 s1, s1, 0xaaab
	s_lshr_b32 s1, s1, 21
	s_mul_i32 s4, s1, 48
	s_sub_i32 s0, s0, s4
	s_lshl_b32 s0, s0, 5
	s_and_b32 s4, s0, 0xffe0
	v_or_b32_e32 v0, s4, v41
	v_readlane_b32 s8, v250, 13
	s_lshl_b32 s5, s1, 6
	v_lshlrev_b32_e32 v14, 2, v0
	v_readlane_b32 s14, v250, 19
	v_readlane_b32 s15, v250, 20
	v_or_b32_e32 v0, s5, v12
	v_cndmask_b32_e64 v1, 0, 1, s[96:97]
	v_lshl_add_u64 v[38:39], s[14:15], 0, v[14:15]
	v_mad_u64_u32 v[2:3], s[0:1], v0, s45, v[38:39]
	global_load_dwordx4 v[108:111], v[2:3], off
	v_readlane_b32 s12, v250, 17
	v_readlane_b32 s13, v250, 18
	v_readlane_b32 s9, v250, 14
	v_readlane_b32 s10, v250, 15
	v_readlane_b32 s11, v250, 16
	v_readlane_b32 s16, v250, 21
	v_readlane_b32 s17, v250, 22
	v_readlane_b32 s18, v250, 23
	v_readlane_b32 s19, v250, 24
	v_readlane_b32 s20, v250, 25
	v_readlane_b32 s21, v250, 26
	v_readlane_b32 s22, v250, 27
	v_readlane_b32 s23, v250, 28
	v_or_b32_e32 v174, s5, v43
	v_mad_u64_u32 v[174:175], s[30:31], v174, s45, v[38:39]
	global_load_dwordx4 v[112:115], v[174:175], off
	v_or_b32_e32 v176, s5, v45
	v_mad_u64_u32 v[176:177], s[30:31], v176, s45, v[38:39]
	global_load_dwordx4 v[116:119], v[176:177], off
	v_or_b32_e32 v178, s5, v47
	v_mad_u64_u32 v[178:179], s[30:31], v178, s45, v[38:39]
	global_load_dwordx4 v[120:123], v[178:179], off
	v_or_b32_e32 v180, s5, v48
	v_mad_u64_u32 v[180:181], s[30:31], v180, s45, v[38:39]
	global_load_dwordx4 v[124:127], v[180:181], off
	v_or_b32_e32 v182, s5, v49
	v_mad_u64_u32 v[182:183], s[30:31], v182, s45, v[38:39]
	global_load_dwordx4 v[128:131], v[182:183], off
	v_or_b32_e32 v184, s5, v50
	v_mad_u64_u32 v[184:185], s[30:31], v184, s45, v[38:39]
	global_load_dwordx4 v[132:135], v[184:185], off
	v_or_b32_e32 v186, s5, v51
	v_mad_u64_u32 v[186:187], s[30:31], v186, s45, v[38:39]
	global_load_dwordx4 v[136:139], v[186:187], off
	s_mov_b32 s30, s82
	s_andn2_b64 vcc, exec, s[96:97]
	s_cbranch_vccnz .Ltr_h_nogain
	v_add_lshl_u32 v14, s5, v12, 2
	global_load_dword v140, v14, s[12:13]
	global_load_dword v142, v14, s[12:13] offset:32
	global_load_dword v144, v14, s[12:13] offset:64
	global_load_dword v146, v14, s[12:13] offset:96
	global_load_dword v148, v14, s[12:13] offset:128
	global_load_dword v150, v14, s[12:13] offset:160
	global_load_dword v152, v14, s[12:13] offset:192
	global_load_dword v154, v14, s[12:13] offset:224
	s_waitcnt vmcnt(0)
	v_pk_mul_f32 v[108:109], v[108:109], v[140:141] op_sel_hi:[1,0]
	v_pk_mul_f32 v[110:111], v[110:111], v[140:141] op_sel_hi:[1,0]
	v_pk_mul_f32 v[112:113], v[112:113], v[142:143] op_sel_hi:[1,0]
	v_pk_mul_f32 v[114:115], v[114:115], v[142:143] op_sel_hi:[1,0]
	v_pk_mul_f32 v[116:117], v[116:117], v[144:145] op_sel_hi:[1,0]
	v_pk_mul_f32 v[118:119], v[118:119], v[144:145] op_sel_hi:[1,0]
	v_pk_mul_f32 v[120:121], v[120:121], v[146:147] op_sel_hi:[1,0]
	v_pk_mul_f32 v[122:123], v[122:123], v[146:147] op_sel_hi:[1,0]
	v_pk_mul_f32 v[124:125], v[124:125], v[148:149] op_sel_hi:[1,0]
	v_pk_mul_f32 v[126:127], v[126:127], v[148:149] op_sel_hi:[1,0]
	v_pk_mul_f32 v[128:129], v[128:129], v[150:151] op_sel_hi:[1,0]
	v_pk_mul_f32 v[130:131], v[130:131], v[150:151] op_sel_hi:[1,0]
	v_pk_mul_f32 v[132:133], v[132:133], v[152:153] op_sel_hi:[1,0]
	v_pk_mul_f32 v[134:135], v[134:135], v[152:153] op_sel_hi:[1,0]
	v_pk_mul_f32 v[136:137], v[136:137], v[154:155] op_sel_hi:[1,0]
	v_pk_mul_f32 v[138:139], v[138:139], v[154:155] op_sel_hi:[1,0]
.Ltr_h_nogain:
	s_waitcnt vmcnt(0)
	ds_write2_b32 v53, v108, v109 offset1:1
	ds_write2_b32 v53, v110, v111 offset0:2 offset1:3
	v_add_u32_e32 v188, v42, v44
	ds_write2_b32 v188, v112, v113 offset1:1
	ds_write2_b32 v188, v114, v115 offset0:2 offset1:3
	v_add_u32_e32 v190, v42, v46
	ds_write2_b32 v190, v116, v117 offset1:1
	ds_write2_b32 v190, v118, v119 offset0:2 offset1:3
	v_add_u32_e32 v188, 0x420, v190
	ds_write2_b32 v188, v120, v121 offset1:1
	v_add_u32_e32 v189, 0x428, v190
	ds_write2_b32 v189, v122, v123 offset1:1
	v_add_u32_e32 v188, 0x840, v190
	ds_write2_b32 v188, v124, v125 offset1:1
	v_add_u32_e32 v189, 0x848, v190
	ds_write2_b32 v189, v126, v127 offset1:1
	v_add_u32_e32 v188, 0xc60, v190
	ds_write2_b32 v188, v128, v129 offset1:1
	v_add_u32_e32 v189, 0xc68, v190
	ds_write2_b32 v189, v130, v131 offset1:1
	v_add_u32_e32 v188, 0x1080, v190
	ds_write2_b32 v188, v132, v133 offset1:1
	v_add_u32_e32 v189, 0x1088, v190
	ds_write2_b32 v189, v134, v135 offset1:1
	v_add_u32_e32 v188, 0x14a0, v190
	ds_write2_b32 v188, v136, v137 offset1:1
	v_add_u32_e32 v189, 0x14a8, v190
	ds_write2_b32 v189, v138, v139 offset1:1
	s_waitcnt lgkmcnt(0)
	ds_read2_b32 v[4:5], v52 offset0:33 offset1:41
	ds_read2_b32 v[6:7], v52 offset1:8
	ds_read2_b32 v[8:9], v52 offset0:66 offset1:74
	ds_read2_b32 v[10:11], v52 offset0:99 offset1:107
	ds_read2_b32 v[38:39], v52 offset0:132 offset1:140
	ds_read2_b32 v[66:67], v52 offset0:165 offset1:173
	ds_read2_b32 v[68:69], v52 offset0:198 offset1:206
	ds_read2_b32 v[70:71], v52 offset0:231 offset1:239
	s_lshl_b32 s28, s5, 1
	s_waitcnt lgkmcnt(6)
	v_cvt_pk_bf16_f32 v0, v6, v4
	v_or_b32_e32 v4, s4, v12
	v_lshl_add_u64 v[72:73], v[30:31], 0, s[28:29]
	v_lshlrev_b32_e32 v14, 11, v4
	s_waitcnt lgkmcnt(4)
	v_cvt_pk_bf16_f32 v1, v8, v10
	s_waitcnt lgkmcnt(2)
	v_cvt_pk_bf16_f32 v2, v38, v66
	s_waitcnt lgkmcnt(0)
	v_cvt_pk_bf16_f32 v3, v68, v70
	v_lshl_add_u64 v[74:75], v[72:73], 0, v[14:15]
	global_store_dwordx4 v[74:75], v[0:3], off
	v_or_b32_e32 v4, s4, v43
	v_lshlrev_b32_e32 v14, 11, v4
	v_cvt_pk_bf16_f32 v0, v7, v5
	v_cvt_pk_bf16_f32 v1, v9, v11
	v_cvt_pk_bf16_f32 v2, v39, v67
	v_cvt_pk_bf16_f32 v3, v69, v71
	ds_read2_b32 v[6:7], v52 offset0:49 offset1:57
	ds_read2_b32 v[8:9], v52 offset0:16 offset1:24
	ds_read2_b32 v[10:11], v52 offset0:82 offset1:90
	ds_read2_b32 v[38:39], v52 offset0:115 offset1:123
	ds_read2_b32 v[66:67], v52 offset0:148 offset1:156
	ds_read2_b32 v[68:69], v52 offset0:181 offset1:189
	ds_read2_b32 v[70:71], v52 offset0:214 offset1:222
	ds_read2_b32 v[74:75], v52 offset0:247 offset1:255
	v_lshl_add_u64 v[4:5], v[72:73], 0, v[14:15]
	global_store_dwordx4 v[4:5], v[0:3], off
	v_or_b32_e32 v4, s4, v45
	v_lshlrev_b32_e32 v14, 11, v4
	s_waitcnt lgkmcnt(6)
	v_cvt_pk_bf16_f32 v0, v8, v6
	s_waitcnt lgkmcnt(4)
	v_cvt_pk_bf16_f32 v1, v10, v38
	s_waitcnt lgkmcnt(2)
	v_cvt_pk_bf16_f32 v2, v66, v68
	s_waitcnt lgkmcnt(0)
	v_cvt_pk_bf16_f32 v3, v70, v74
	v_lshl_add_u64 v[4:5], v[72:73], 0, v[14:15]
	global_store_dwordx4 v[4:5], v[0:3], off
	v_or_b32_e32 v4, s4, v47
	v_lshlrev_b32_e32 v14, 11, v4
	v_cvt_pk_bf16_f32 v0, v9, v7
	v_cvt_pk_bf16_f32 v1, v11, v39
	v_cvt_pk_bf16_f32 v2, v67, v69
	v_cvt_pk_bf16_f32 v3, v71, v75
	v_lshl_add_u64 v[4:5], v[72:73], 0, v[14:15]
	global_store_dwordx4 v[4:5], v[0:3], off
	s_waitcnt lgkmcnt(0)

.LBB0_95:
	s_andn2_b64 vcc, exec, s[0:1]
	s_cbranch_vccnz .LBB0_23
	s_mul_hi_i32 s0, s47, 0x4ec4ec4f
	s_lshr_b32 s1, s0, 31
	s_ashr_i32 s30, s0, 5
	s_add_i32 s30, s30, s1
	s_mul_i32 s28, s30, 0xfffff300
	s_add_i32 s28, s28, s38
	v_add_u32_e32 v0, s28, v41
	s_movk_i32 s0, 0xc00
	v_add_u32_e32 v1, 8, v0
	v_cmp_gt_i32_e32 vcc, s0, v0
	s_nop 1
	v_cndmask_b32_e32 v14, v1, v0, vcc
	s_mov_b64 s[4:5], 0
	s_lshl_b32 s30, s30, 6
	v_lshl_add_u64 v[8:9], v[14:15], 2, s[64:65]
	v_or_b32_e32 v172, s30, v12
	v_mad_i64_i32 v[172:173], s[48:49], v172, s46, v[8:9]
	global_load_dwordx4 v[108:111], v[172:173], off
	v_or_b32_e32 v174, s30, v43
	v_mad_i64_i32 v[174:175], s[48:49], v174, s46, v[8:9]
	global_load_dwordx4 v[112:115], v[174:175], off
	v_or_b32_e32 v176, s30, v45
	v_mad_i64_i32 v[176:177], s[48:49], v176, s46, v[8:9]
	global_load_dwordx4 v[116:119], v[176:177], off
	v_or_b32_e32 v178, s30, v47
	v_mad_i64_i32 v[178:179], s[48:49], v178, s46, v[8:9]
	global_load_dwordx4 v[120:123], v[178:179], off
	v_or_b32_e32 v180, s30, v48
	v_mad_i64_i32 v[180:181], s[48:49], v180, s46, v[8:9]
	global_load_dwordx4 v[124:127], v[180:181], off
	v_or_b32_e32 v182, s30, v49
	v_mad_i64_i32 v[182:183], s[48:49], v182, s46, v[8:9]
	global_load_dwordx4 v[128:131], v[182:183], off
	v_or_b32_e32 v184, s30, v50
	v_mad_i64_i32 v[184:185], s[48:49], v184, s46, v[8:9]
	global_load_dwordx4 v[132:135], v[184:185], off
	v_or_b32_e32 v186, s30, v51
	v_mad_i64_i32 v[186:187], s[48:49], v186, s46, v[8:9]
	global_load_dwordx4 v[136:139], v[186:187], off
	s_andn2_b64 vcc, exec, s[26:27]
	s_cbranch_vccnz .Ltr_k_nogain
	s_ashr_i32 s31, s30, 31
	v_lshl_add_u64 v[4:5], s[30:31], 0, v[12:13]
	v_lshl_add_u64 v[4:5], v[4:5], 2, s[60:61]
	global_load_dword v140, v[4:5], off
	global_load_dword v142, v[4:5], off offset:32
	global_load_dword v144, v[4:5], off offset:64
	global_load_dword v146, v[4:5], off offset:96
	global_load_dword v148, v[4:5], off offset:128
	global_load_dword v150, v[4:5], off offset:160
	global_load_dword v152, v[4:5], off offset:192
	global_load_dword v154, v[4:5], off offset:224
	s_waitcnt vmcnt(0)
	v_pk_mul_f32 v[108:109], v[108:109], v[140:141] op_sel_hi:[1,0]
	v_pk_mul_f32 v[110:111], v[110:111], v[140:141] op_sel_hi:[1,0]
	v_pk_mul_f32 v[112:113], v[112:113], v[142:143] op_sel_hi:[1,0]
	v_pk_mul_f32 v[114:115], v[114:115], v[142:143] op_sel_hi:[1,0]
	v_pk_mul_f32 v[116:117], v[116:117], v[144:145] op_sel_hi:[1,0]
	v_pk_mul_f32 v[118:119], v[118:119], v[144:145] op_sel_hi:[1,0]
	v_pk_mul_f32 v[120:121], v[120:121], v[146:147] op_sel_hi:[1,0]
	v_pk_mul_f32 v[122:123], v[122:123], v[146:147] op_sel_hi:[1,0]
	v_pk_mul_f32 v[124:125], v[124:125], v[148:149] op_sel_hi:[1,0]
	v_pk_mul_f32 v[126:127], v[126:127], v[148:149] op_sel_hi:[1,0]
	v_pk_mul_f32 v[128:129], v[128:129], v[150:151] op_sel_hi:[1,0]
	v_pk_mul_f32 v[130:131], v[130:131], v[150:151] op_sel_hi:[1,0]
	v_pk_mul_f32 v[132:133], v[132:133], v[152:153] op_sel_hi:[1,0]
	v_pk_mul_f32 v[134:135], v[134:135], v[152:153] op_sel_hi:[1,0]
	v_pk_mul_f32 v[136:137], v[136:137], v[154:155] op_sel_hi:[1,0]
	v_pk_mul_f32 v[138:139], v[138:139], v[154:155] op_sel_hi:[1,0]
.Ltr_k_nogain:
	s_waitcnt vmcnt(0)
	ds_write2_b32 v53, v108, v109 offset1:1
	ds_write2_b32 v53, v110, v111 offset0:2 offset1:3
	v_add_u32_e32 v188, v42, v44
	ds_write2_b32 v188, v112, v113 offset1:1
	ds_write2_b32 v188, v114, v115 offset0:2 offset1:3
	v_add_u32_e32 v10, v42, v46
	ds_write2_b32 v10, v116, v117 offset1:1
	ds_write2_b32 v10, v118, v119 offset0:2 offset1:3
	v_add_u32_e32 v188, 0x420, v10
	ds_write2_b32 v188, v120, v121 offset1:1
	v_add_u32_e32 v189, 0x428, v10
	ds_write2_b32 v189, v122, v123 offset1:1
	v_add_u32_e32 v188, 0x840, v10
	ds_write2_b32 v188, v124, v125 offset1:1
	v_add_u32_e32 v189, 0x848, v10
	ds_write2_b32 v189, v126, v127 offset1:1
	v_add_u32_e32 v188, 0xc60, v10
	ds_write2_b32 v188, v128, v129 offset1:1
	v_add_u32_e32 v189, 0xc68, v10
	ds_write2_b32 v189, v130, v131 offset1:1
	v_add_u32_e32 v188, 0x1080, v10
	ds_write2_b32 v188, v132, v133 offset1:1
	v_add_u32_e32 v189, 0x1088, v10
	ds_write2_b32 v189, v134, v135 offset1:1
	v_mov_b64_e32 v[0:1], v[136:137]
	v_mov_b64_e32 v[2:3], v[138:139]
	s_branch .LBB0_22

.LBB0_423:
	s_or_b64 exec, exec, s[62:63]
	v_lshl_add_u64 v[48:49], s[88:89], 0, v[34:35]
	s_and_saveexec_b64 s[62:63], s[0:1]
	s_cbranch_execz .LBB0_425
	v_add_co_u32_e32 v84, vcc, 0x3f00000, v48
	s_nop 1
	v_addc_co_u32_e32 v85, vcc, 0, v49, vcc
	v_add_co_u32_e32 v86, vcc, 0x3f02000, v48
	s_nop 1
	v_addc_co_u32_e32 v87, vcc, 0, v49, vcc
	s_waitcnt vmcnt(2)
	v_mov_b32_e32 v79, v81
	v_mov_b32_e32 v80, v82
	v_add_co_u32_e32 v84, vcc, 0x3d00000, v42
	v_max_f32_e32 v83, v79, v79
	v_add_f32_e32 v80, v58, v80
	v_max_f32_e32 v58, v80, v83
	v_sub_f32_e32 v80, v80, v58
	v_sub_f32_e32 v79, v79, v58
	v_mul_f32_e32 v80, 0x3fb8aa3b, v80
	v_mul_f32_e32 v79, 0x3fb8aa3b, v79
	v_exp_f32_e32 v86, v80
	v_exp_f32_e32 v87, v79
	v_addc_co_u32_e32 v85, vcc, 0, v43, vcc
	global_store_dword v[84:85], v40, off
	v_pk_mul_f32 v[40:41], v[40:41], v[86:87]
	s_nop 0
	v_add_f32_e32 v40, v40, v41

.LBB0_427:
	s_or_b64 exec, exec, s[62:63]
	s_and_saveexec_b64 s[62:63], s[0:1]
	s_cbranch_execz .LBB0_429
	v_add_co_u32_e32 v56, vcc, 0x3f00000, v48
	s_nop 1
	v_addc_co_u32_e32 v57, vcc, 0, v49, vcc
	v_add_co_u32_e32 v82, vcc, 0x3f02000, v48
	s_nop 1
	v_addc_co_u32_e32 v83, vcc, 0, v49, vcc
	s_waitcnt vmcnt(2)
	v_mov_b32_e32 v41, v79
	v_mov_b32_e32 v55, v80
	v_add_co_u32_e32 v56, vcc, 0x3d00000, v42
	v_max_f32_e32 v57, v41, v41
	v_add_f32_e32 v55, v58, v55
	v_max_f32_e32 v58, v55, v57
	v_sub_f32_e32 v55, v55, v58
	v_sub_f32_e32 v41, v41, v58
	v_mul_f32_e32 v55, 0x3fb8aa3b, v55
	v_mul_f32_e32 v41, 0x3fb8aa3b, v41
	v_exp_f32_e32 v82, v55
	v_exp_f32_e32 v83, v41
	v_addc_co_u32_e32 v57, vcc, 0, v43, vcc
	v_mov_b32_e32 v41, v77
	global_store_dword v[56:57], v40, off offset:768
	v_pk_mul_f32 v[40:41], v[40:41], v[82:83]
	s_nop 0
	v_add_f32_e32 v40, v40, v41

.LBB0_431:
	s_or_b64 exec, exec, s[62:63]
	s_and_saveexec_b64 s[62:63], s[0:1]
	s_cbranch_execz .LBB0_433
	v_add_co_u32_e32 v24, vcc, 0x3f00000, v48
	v_mov_b32_e32 v41, v73
	s_nop 0
	v_addc_co_u32_e32 v25, vcc, 0, v49, vcc
	v_add_co_u32_e32 v26, vcc, 0x3f02000, v48
	s_nop 1
	v_addc_co_u32_e32 v27, vcc, 0, v49, vcc
	s_waitcnt vmcnt(2)
	v_mov_b32_e32 v25, v55
	s_nop 0
	v_mov_b32_e32 v26, v56
	v_add_co_u32_e32 v24, vcc, 0x3d00000, v42
	v_max_f32_e32 v27, v25, v25
	v_add_f32_e32 v26, v58, v26
	v_max_f32_e32 v58, v26, v27
	v_sub_f32_e32 v26, v26, v58
	v_sub_f32_e32 v25, v25, v58
	v_mul_f32_e32 v26, 0x3fb8aa3b, v26
	v_mul_f32_e32 v25, 0x3fb8aa3b, v25
	v_exp_f32_e32 v26, v26
	v_exp_f32_e32 v27, v25
	v_addc_co_u32_e32 v25, vcc, 0, v43, vcc
	global_store_dword v[24:25], v40, off offset:1536
	v_pk_mul_f32 v[24:25], v[40:41], v[26:27]
	s_nop 0
	v_add_f32_e32 v40, v24, v25

.LBB0_435:
	s_or_b64 exec, exec, s[62:63]
	s_and_saveexec_b64 s[62:63], s[0:1]
	s_cbranch_execz .LBB0_437
	v_add_co_u32_e32 v28, vcc, 0x3f00000, v48
	s_nop 1
	v_addc_co_u32_e32 v29, vcc, 0, v49, vcc
	v_add_co_u32_e32 v50, vcc, 0x3f02000, v48
	s_nop 1
	v_addc_co_u32_e32 v51, vcc, 0, v49, vcc
	s_waitcnt vmcnt(2)
	v_mov_b32_e32 v29, v54
	s_nop 0
	v_mov_b32_e32 v31, v57
	v_add_co_u32_e32 v28, vcc, 0x3d00000, v42
	v_max_f32_e32 v41, v29, v29
	v_add_f32_e32 v31, v58, v31
	v_max_f32_e32 v58, v31, v41
	v_sub_f32_e32 v31, v31, v58
	v_sub_f32_e32 v29, v29, v58
	v_mul_f32_e32 v31, 0x3fb8aa3b, v31
	v_mul_f32_e32 v29, 0x3fb8aa3b, v29
	v_exp_f32_e32 v50, v31
	v_exp_f32_e32 v51, v29
	v_addc_co_u32_e32 v29, vcc, 0, v43, vcc
	v_mov_b32_e32 v41, v71
	global_store_dword v[28:29], v40, off offset:2304
	v_pk_mul_f32 v[28:29], v[40:41], v[50:51]
	s_nop 0
	v_add_f32_e32 v40, v28, v29

.LBB0_439:
	s_or_b64 exec, exec, s[62:63]
	s_and_saveexec_b64 s[62:63], s[0:1]
	s_cbranch_execz .LBB0_441
	v_add_co_u32_e32 v26, vcc, 0x3f00000, v48
	v_mov_b32_e32 v41, v69
	s_nop 0
	v_addc_co_u32_e32 v27, vcc, 0, v49, vcc
	v_add_co_u32_e32 v50, vcc, 0x3f02000, v48
	s_nop 1
	v_addc_co_u32_e32 v51, vcc, 0, v49, vcc
	s_waitcnt vmcnt(2)
	v_mov_b32_e32 v22, v28
	s_nop 0
	v_mov_b32_e32 v27, v29
	v_add_co_u32_e32 v26, vcc, 0x3d00000, v42
	v_max_f32_e32 v30, v22, v22
	v_add_f32_e32 v27, v58, v27
	v_max_f32_e32 v58, v27, v30
	v_sub_f32_e32 v27, v27, v58
	v_sub_f32_e32 v22, v22, v58
	v_mul_f32_e32 v27, 0x3fb8aa3b, v27
	v_mul_f32_e32 v22, 0x3fb8aa3b, v22
	v_exp_f32_e32 v50, v27
	v_exp_f32_e32 v51, v22
	v_addc_co_u32_e32 v27, vcc, 0, v43, vcc
	global_store_dword v[26:27], v40, off offset:3072
	v_pk_mul_f32 v[26:27], v[40:41], v[50:51]
	s_nop 0
	v_add_f32_e32 v40, v26, v27

.LBB0_443:
	s_or_b64 exec, exec, s[62:63]
	s_and_saveexec_b64 s[62:63], s[0:1]
	s_cbranch_execz .LBB0_445
	v_add_co_u32_e32 v16, vcc, 0x3f00000, v48
	v_mov_b32_e32 v41, v67
	s_nop 0
	v_addc_co_u32_e32 v17, vcc, 0, v49, vcc
	v_add_co_u32_e32 v28, vcc, 0x3f02000, v48
	s_nop 1
	v_addc_co_u32_e32 v29, vcc, 0, v49, vcc
	s_waitcnt vmcnt(2)
	v_mov_b32_e32 v17, v22
	s_nop 0
	v_mov_b32_e32 v23, v26
	v_add_co_u32_e32 v16, vcc, 0x3d00000, v42
	v_max_f32_e32 v24, v17, v17
	v_add_f32_e32 v23, v58, v23
	v_max_f32_e32 v58, v23, v24
	v_sub_f32_e32 v23, v23, v58
	v_sub_f32_e32 v17, v17, v58
	v_mul_f32_e32 v23, 0x3fb8aa3b, v23
	v_mul_f32_e32 v17, 0x3fb8aa3b, v17
	v_exp_f32_e32 v28, v23
	v_exp_f32_e32 v29, v17
	v_addc_co_u32_e32 v17, vcc, 0, v43, vcc
	global_store_dword v[16:17], v40, off offset:3840
	v_pk_mul_f32 v[16:17], v[40:41], v[28:29]
	s_nop 0
	v_add_f32_e32 v40, v16, v17

.LBB0_447:
	s_or_b64 exec, exec, s[62:63]
	s_and_saveexec_b64 s[62:63], s[0:1]
	s_cbranch_execz .LBB0_449
	v_add_co_u32_e32 v14, vcc, 0x3f00000, v48
	v_mov_b32_e32 v41, v65
	s_nop 0
	v_addc_co_u32_e32 v15, vcc, 0, v49, vcc
	v_add_co_u32_e32 v20, vcc, 0x3f02000, v48
	s_nop 1
	v_addc_co_u32_e32 v21, vcc, 0, v49, vcc
	s_waitcnt vmcnt(2)
	v_mov_b32_e32 v15, v23
	s_nop 0
	v_mov_b32_e32 v19, v24
	v_add_co_u32_e32 v14, vcc, 0x3d01000, v42
	v_max_f32_e32 v20, v15, v15
	v_add_f32_e32 v19, v58, v19
	v_max_f32_e32 v58, v19, v20
	v_sub_f32_e32 v19, v19, v58
	v_sub_f32_e32 v15, v15, v58
	v_mul_f32_e32 v19, 0x3fb8aa3b, v19
	v_mul_f32_e32 v15, 0x3fb8aa3b, v15
	v_exp_f32_e32 v20, v19
	v_exp_f32_e32 v21, v15
	v_addc_co_u32_e32 v15, vcc, 0, v43, vcc
	global_store_dword v[14:15], v40, off offset:512
	v_pk_mul_f32 v[14:15], v[40:41], v[20:21]
	s_nop 0
	v_add_f32_e32 v40, v14, v15

.LBB0_451:
	s_or_b64 exec, exec, s[62:63]
	s_and_saveexec_b64 s[54:55], s[0:1]
	s_cbranch_execz .LBB0_404
	v_add_co_u32_e32 v10, vcc, 0x3f00000, v48
	v_mov_b32_e32 v41, v63
	s_nop 0
	v_addc_co_u32_e32 v11, vcc, 0, v49, vcc
	v_add_co_u32_e32 v12, vcc, 0x3f02000, v48
	s_nop 1
	v_addc_co_u32_e32 v13, vcc, 0, v49, vcc
	s_waitcnt vmcnt(2)
	v_mov_b32_e32 v7, v19
	s_nop 0
	v_mov_b32_e32 v11, v20
	v_add_co_u32_e32 v10, vcc, 0x3d01000, v42
	v_max_f32_e32 v12, v7, v7
	v_add_f32_e32 v11, v58, v11
	v_max_f32_e32 v58, v11, v12
	v_sub_f32_e32 v11, v11, v58
	v_sub_f32_e32 v7, v7, v58
	v_mul_f32_e32 v11, 0x3fb8aa3b, v11
	v_mul_f32_e32 v7, 0x3fb8aa3b, v7
	v_exp_f32_e32 v12, v11
	v_exp_f32_e32 v13, v7
	v_addc_co_u32_e32 v11, vcc, 0, v43, vcc
	global_store_dword v[10:11], v40, off offset:1280
	v_pk_mul_f32 v[10:11], v[40:41], v[12:13]
	s_nop 0
	v_add_f32_e32 v40, v10, v11
	s_branch .LBB0_404

.LBB0_965:
	v_lshl_add_u32 v140, s26, 8, v143
	v_cndmask_b32_e64 v141, 0, 1, s[72:73]
	v_mov_b32_e32 v142, 1.0
	v_cmp_ne_u32_e64 s[38:39], 1, v141
	s_andn2_b64 vcc, exec, s[72:73]
	v_ashrrev_i32_e32 v141, 31, v140
	v_mov_b32_e32 v144, 1.0
	s_movk_i32 s40, 0xa00
	s_cbranch_vccnz .LBB0_967
	v_lshlrev_b64 v[150:151], 6, v[140:141]
	v_lshl_add_u64 v[150:151], v[134:135], 0, v[150:151]
	global_load_dwordx4 v[206:209], v[150:151], off
	global_load_dwordx4 v[210:213], v[150:151], off offset:1024
	global_load_dwordx4 v[214:217], v[150:151], off offset:2048
	global_load_dwordx4 v[218:221], v[150:151], off offset:3072
	v_add_co_u32_e32 v238, vcc, 0x2000, v150
	s_nop 1
	v_addc_co_u32_e32 v239, vcc, 0, v151, vcc
	global_load_dwordx4 v[222:225], v[238:239], off
	global_load_dwordx4 v[226:229], v[238:239], off offset:1024
	global_load_dwordx4 v[230:233], v[238:239], off offset:2048
	global_load_dwordx4 v[234:237], v[238:239], off offset:3072
	v_and_b32_e32 v148, 64, v191
	v_xor_b32_e32 v146, 16, v191
	v_add_u32_e32 v148, 64, v148
	v_cmp_lt_i32_e32 vcc, v146, v148
	s_waitcnt vmcnt(0)
	v_mov_b64_e32 v[168:169], v[206:207]
	v_mov_b64_e32 v[170:171], v[208:209]
	v_mov_b32_e32 v150, v169
	v_mov_b32_e32 v151, v170
	v_mov_b32_e32 v169, v171
	v_pk_add_f32 v[150:151], v[150:151], v[168:169]
	v_cndmask_b32_e32 v146, v191, v146, vcc
	v_add_f32_e32 v144, v150, v151
	v_lshlrev_b32_e32 v146, 2, v146
	ds_bpermute_b32 v146, v146, v144
	s_waitcnt lgkmcnt(0)
	v_add_f32_e32 v144, v144, v146
	v_xor_b32_e32 v146, 32, v191
	v_cmp_lt_i32_e32 vcc, v146, v148
	s_nop 1
	v_cndmask_b32_e32 v146, v191, v146, vcc
	v_lshlrev_b32_e32 v146, 2, v146
	ds_bpermute_b32 v146, v146, v144
	s_waitcnt lgkmcnt(0)
	v_add_f32_e32 v144, v144, v146
	v_fmamk_f32 v144, v144, 0x3a800000, v154
	v_cmp_gt_f32_e32 vcc, s84, v144
	v_mul_f32_e32 v146, 0x4b800000, v144
	s_nop 0
	v_cndmask_b32_e32 v144, v144, v146, vcc
	v_rsq_f32_e32 v144, v144
	s_nop 0
	v_mul_f32_e32 v146, 0x45800000, v144
	v_cndmask_b32_e32 v144, v144, v146, vcc
.LBB0_967:
	s_and_b64 vcc, exec, s[38:39]
	s_cbranch_vccnz .LBB0_969
	v_or_b32_e32 v150, 16, v140
	v_ashrrev_i32_e32 v151, 31, v150
	v_lshlrev_b64 v[150:151], 6, v[150:151]
	v_lshl_add_u64 v[150:151], v[134:135], 0, v[150:151]
	s_waitcnt vmcnt(0)
	v_mov_b64_e32 v[168:169], v[210:211]
	v_mov_b64_e32 v[170:171], v[212:213]
	v_and_b32_e32 v148, 64, v191
	v_xor_b32_e32 v146, 16, v191
	v_add_u32_e32 v148, 64, v148
	v_cmp_lt_i32_e32 vcc, v146, v148
	s_waitcnt vmcnt(0)
	v_mov_b32_e32 v150, v169
	v_mov_b32_e32 v151, v170
	v_mov_b32_e32 v169, v171
	v_pk_add_f32 v[150:151], v[150:151], v[168:169]
	v_cndmask_b32_e32 v146, v191, v146, vcc
	v_add_f32_e32 v142, v150, v151
	v_lshlrev_b32_e32 v146, 2, v146
	ds_bpermute_b32 v146, v146, v142
	s_waitcnt lgkmcnt(0)
	v_add_f32_e32 v142, v142, v146
	v_xor_b32_e32 v146, 32, v191
	v_cmp_lt_i32_e32 vcc, v146, v148
	s_nop 1
	v_cndmask_b32_e32 v146, v191, v146, vcc
	v_lshlrev_b32_e32 v146, 2, v146
	ds_bpermute_b32 v146, v146, v142
	s_waitcnt lgkmcnt(0)
	v_add_f32_e32 v142, v142, v146
	v_fmamk_f32 v142, v142, 0x3a800000, v154
	v_cmp_gt_f32_e32 vcc, s84, v142
	v_mul_f32_e32 v146, 0x4b800000, v142
	s_nop 0
	v_cndmask_b32_e32 v142, v142, v146, vcc
	v_rsq_f32_e32 v142, v142
	s_nop 0
	v_mul_f32_e32 v146, 0x45800000, v142
	v_cndmask_b32_e32 v142, v142, v146, vcc
.LBB0_969:
	v_mov_b32_e32 v146, 1.0
	s_and_b64 vcc, exec, s[38:39]
	v_mov_b32_e32 v148, 1.0
	s_cbranch_vccnz .LBB0_971
	v_or_b32_e32 v150, 32, v140
	v_ashrrev_i32_e32 v151, 31, v150
	v_lshlrev_b64 v[150:151], 6, v[150:151]
	v_lshl_add_u64 v[150:151], v[134:135], 0, v[150:151]
	s_waitcnt vmcnt(0)
	v_mov_b64_e32 v[168:169], v[214:215]
	v_mov_b64_e32 v[170:171], v[216:217]
	s_waitcnt vmcnt(0)
	v_mov_b32_e32 v150, v169
	v_mov_b32_e32 v151, v170
	v_mov_b32_e32 v169, v171
	v_pk_add_f32 v[150:151], v[150:151], v[168:169]
	s_nop 0
	v_add_f32_e32 v148, v150, v151
	v_and_b32_e32 v151, 64, v191
	v_xor_b32_e32 v150, 16, v191
	v_add_u32_e32 v151, 64, v151
	v_cmp_lt_i32_e32 vcc, v150, v151
	s_nop 1
	v_cndmask_b32_e32 v150, v191, v150, vcc
	v_lshlrev_b32_e32 v150, 2, v150
	ds_bpermute_b32 v150, v150, v148
	s_waitcnt lgkmcnt(0)
	v_add_f32_e32 v148, v148, v150
	v_xor_b32_e32 v150, 32, v191
	v_cmp_lt_i32_e32 vcc, v150, v151
	s_nop 1
	v_cndmask_b32_e32 v150, v191, v150, vcc
	v_lshlrev_b32_e32 v150, 2, v150
	ds_bpermute_b32 v150, v150, v148
	s_waitcnt lgkmcnt(0)
	v_add_f32_e32 v148, v148, v150
	v_fmamk_f32 v148, v148, 0x3a800000, v154
	v_cmp_gt_f32_e32 vcc, s84, v148
	v_mul_f32_e32 v150, 0x4b800000, v148
	s_nop 0
	v_cndmask_b32_e32 v148, v148, v150, vcc
	v_rsq_f32_e32 v148, v148
	s_nop 0
	v_mul_f32_e32 v150, 0x45800000, v148
	v_cndmask_b32_e32 v148, v148, v150, vcc
.LBB0_971:
	s_and_b64 vcc, exec, s[38:39]
	s_cbranch_vccnz .LBB0_973
	v_or_b32_e32 v150, 48, v140
	v_ashrrev_i32_e32 v151, 31, v150
	v_lshlrev_b64 v[150:151], 6, v[150:151]
	v_lshl_add_u64 v[150:151], v[134:135], 0, v[150:151]
	s_waitcnt vmcnt(0)
	v_mov_b64_e32 v[168:169], v[218:219]
	v_mov_b64_e32 v[170:171], v[220:221]
	s_waitcnt vmcnt(0)
	v_mov_b32_e32 v150, v169
	v_mov_b32_e32 v151, v170
	v_mov_b32_e32 v169, v171
	v_pk_add_f32 v[150:151], v[150:151], v[168:169]
	s_nop 0
	v_add_f32_e32 v146, v150, v151
	v_and_b32_e32 v151, 64, v191
	v_xor_b32_e32 v150, 16, v191
	v_add_u32_e32 v151, 64, v151
	v_cmp_lt_i32_e32 vcc, v150, v151
	s_nop 1
	v_cndmask_b32_e32 v150, v191, v150, vcc
	v_lshlrev_b32_e32 v150, 2, v150
	ds_bpermute_b32 v150, v150, v146
	s_waitcnt lgkmcnt(0)
	v_add_f32_e32 v146, v146, v150
	v_xor_b32_e32 v150, 32, v191
	v_cmp_lt_i32_e32 vcc, v150, v151
	s_nop 1
	v_cndmask_b32_e32 v150, v191, v150, vcc
	v_lshlrev_b32_e32 v150, 2, v150
	ds_bpermute_b32 v150, v150, v146
	s_waitcnt lgkmcnt(0)
	v_add_f32_e32 v146, v146, v150
	v_fmamk_f32 v146, v146, 0x3a800000, v154
	v_cmp_gt_f32_e32 vcc, s84, v146
	v_mul_f32_e32 v150, 0x4b800000, v146
	s_nop 0
	v_cndmask_b32_e32 v146, v146, v150, vcc
	v_rsq_f32_e32 v146, v146
	s_nop 0
	v_mul_f32_e32 v150, 0x45800000, v146
	v_cndmask_b32_e32 v146, v146, v150, vcc
.LBB0_973:
	v_mov_b32_e32 v150, 1.0
	s_and_b64 vcc, exec, s[38:39]
	v_mov_b32_e32 v168, 1.0
	s_cbranch_vccnz .LBB0_975
	v_lshlrev_b64 v[168:169], 6, v[140:141]
	v_lshl_add_u64 v[168:169], v[134:135], 0, v[168:169]
	v_add_co_u32_e32 v168, vcc, 0x2000, v168
	s_nop 1
	v_addc_co_u32_e32 v169, vcc, 0, v169, vcc
	s_waitcnt vmcnt(0)
	v_mov_b64_e32 v[168:169], v[222:223]
	v_mov_b64_e32 v[170:171], v[224:225]
	s_waitcnt vmcnt(0)
	v_mov_b32_e32 v172, v169
	v_mov_b32_e32 v173, v170
	v_mov_b32_e32 v169, v171
	v_pk_add_f32 v[168:169], v[172:173], v[168:169]
	s_nop 0
	v_add_f32_e32 v151, v168, v169
	v_and_b32_e32 v169, 64, v191
	v_xor_b32_e32 v168, 16, v191
	v_add_u32_e32 v169, 64, v169
	v_cmp_lt_i32_e32 vcc, v168, v169
	s_nop 1
	v_cndmask_b32_e32 v168, v191, v168, vcc
	v_lshlrev_b32_e32 v168, 2, v168
	ds_bpermute_b32 v168, v168, v151
	s_waitcnt lgkmcnt(0)
	v_add_f32_e32 v151, v151, v168
	v_xor_b32_e32 v168, 32, v191
	v_cmp_lt_i32_e32 vcc, v168, v169
	s_nop 1
	v_cndmask_b32_e32 v168, v191, v168, vcc
	v_lshlrev_b32_e32 v168, 2, v168
	ds_bpermute_b32 v168, v168, v151
	s_waitcnt lgkmcnt(0)
	v_add_f32_e32 v151, v151, v168
	v_fmamk_f32 v151, v151, 0x3a800000, v154
	v_cmp_gt_f32_e32 vcc, s84, v151
	v_mul_f32_e32 v168, 0x4b800000, v151
	s_nop 0
	v_cndmask_b32_e32 v151, v151, v168, vcc
	v_rsq_f32_e32 v151, v151
	s_nop 0
	v_mul_f32_e32 v168, 0x45800000, v151
	v_cndmask_b32_e32 v168, v151, v168, vcc
.LBB0_975:
	s_and_b64 vcc, exec, s[38:39]
	s_cbranch_vccnz .LBB0_977
	v_lshlrev_b64 v[150:151], 6, v[140:141]
	v_lshl_add_u64 v[150:151], v[134:135], 0, v[150:151]
	v_add_co_u32_e32 v150, vcc, 0x2000, v150
	v_and_b32_e32 v169, 64, v191
	s_nop 0
	v_addc_co_u32_e32 v151, vcc, 0, v151, vcc
	s_waitcnt vmcnt(0)
	v_mov_b64_e32 v[170:171], v[226:227]
	v_mov_b64_e32 v[172:173], v[228:229]
	v_add_u32_e32 v169, 64, v169
	s_waitcnt vmcnt(0)
	v_mov_b32_e32 v150, v171
	v_mov_b32_e32 v151, v172
	v_mov_b32_e32 v171, v173
	v_pk_add_f32 v[150:151], v[150:151], v[170:171]
	s_nop 0
	v_add_f32_e32 v150, v150, v151
	v_xor_b32_e32 v151, 16, v191
	v_cmp_lt_i32_e32 vcc, v151, v169
	s_nop 1
	v_cndmask_b32_e32 v151, v191, v151, vcc
	v_lshlrev_b32_e32 v151, 2, v151
	ds_bpermute_b32 v151, v151, v150
	s_waitcnt lgkmcnt(0)
	v_add_f32_e32 v150, v150, v151
	v_xor_b32_e32 v151, 32, v191
	v_cmp_lt_i32_e32 vcc, v151, v169
	s_nop 1
	v_cndmask_b32_e32 v151, v191, v151, vcc
	v_lshlrev_b32_e32 v151, 2, v151
	ds_bpermute_b32 v151, v151, v150
	s_waitcnt lgkmcnt(0)
	v_add_f32_e32 v150, v150, v151
	v_fmamk_f32 v150, v150, 0x3a800000, v154
	v_cmp_gt_f32_e32 vcc, s84, v150
	v_mul_f32_e32 v151, 0x4b800000, v150
	s_nop 0
	v_cndmask_b32_e32 v150, v150, v151, vcc
	v_rsq_f32_e32 v150, v150
	s_nop 0
	v_mul_f32_e32 v151, 0x45800000, v150
	v_cndmask_b32_e32 v150, v150, v151, vcc
.LBB0_977:
	v_mov_b32_e32 v170, 1.0
	s_and_b64 vcc, exec, s[38:39]
	v_mov_b32_e32 v172, 1.0
	s_cbranch_vccnz .LBB0_979
	v_lshlrev_b64 v[172:173], 6, v[140:141]
	v_lshl_add_u64 v[172:173], v[134:135], 0, v[172:173]
	v_add_co_u32_e32 v172, vcc, 0x2000, v172
	v_and_b32_e32 v171, 64, v191
	s_nop 0
	v_addc_co_u32_e32 v173, vcc, 0, v173, vcc
	s_waitcnt vmcnt(0)
	v_mov_b64_e32 v[172:173], v[230:231]
	v_mov_b64_e32 v[174:175], v[232:233]
	v_xor_b32_e32 v169, 16, v191
	v_add_u32_e32 v171, 64, v171
	v_cmp_lt_i32_e32 vcc, v169, v171
	s_waitcnt vmcnt(0)
	v_mov_b32_e32 v176, v173
	v_mov_b32_e32 v177, v174
	v_mov_b32_e32 v173, v175
	v_pk_add_f32 v[172:173], v[176:177], v[172:173]
	v_cndmask_b32_e32 v169, v191, v169, vcc
	v_add_f32_e32 v151, v172, v173
	v_lshlrev_b32_e32 v169, 2, v169
	ds_bpermute_b32 v169, v169, v151
	s_waitcnt lgkmcnt(0)
	v_add_f32_e32 v151, v151, v169
	v_xor_b32_e32 v169, 32, v191
	v_cmp_lt_i32_e32 vcc, v169, v171
	s_nop 1
	v_cndmask_b32_e32 v169, v191, v169, vcc
	v_lshlrev_b32_e32 v169, 2, v169
	ds_bpermute_b32 v169, v169, v151
	s_waitcnt lgkmcnt(0)
	v_add_f32_e32 v151, v151, v169
	v_fmamk_f32 v151, v151, 0x3a800000, v154
	v_cmp_gt_f32_e32 vcc, s84, v151
	v_mul_f32_e32 v169, 0x4b800000, v151
	s_nop 0
	v_cndmask_b32_e32 v151, v151, v169, vcc
	v_rsq_f32_e32 v151, v151
	s_nop 0
	v_mul_f32_e32 v169, 0x45800000, v151
	v_cndmask_b32_e32 v172, v151, v169, vcc
.LBB0_979:
	s_and_b64 vcc, exec, s[38:39]
	s_cbranch_vccnz .LBB0_981
	v_lshlrev_b64 v[170:171], 6, v[140:141]
	v_lshl_add_u64 v[170:171], v[134:135], 0, v[170:171]
	v_add_co_u32_e32 v170, vcc, 0x2000, v170
	v_and_b32_e32 v169, 64, v191
	s_nop 0
	v_addc_co_u32_e32 v171, vcc, 0, v171, vcc
	s_waitcnt vmcnt(0)
	v_mov_b64_e32 v[174:175], v[234:235]
	v_mov_b64_e32 v[176:177], v[236:237]
	v_xor_b32_e32 v151, 16, v191
	v_add_u32_e32 v169, 64, v169
	v_cmp_lt_i32_e32 vcc, v151, v169
	s_waitcnt vmcnt(0)
	v_mov_b32_e32 v170, v175
	v_mov_b32_e32 v171, v176
	v_mov_b32_e32 v175, v177
	v_pk_add_f32 v[170:171], v[170:171], v[174:175]
	v_cndmask_b32_e32 v151, v191, v151, vcc
	v_add_f32_e32 v141, v170, v171
	v_lshlrev_b32_e32 v151, 2, v151
	ds_bpermute_b32 v151, v151, v141
	s_waitcnt lgkmcnt(0)
	v_add_f32_e32 v141, v141, v151
	v_xor_b32_e32 v151, 32, v191
	v_cmp_lt_i32_e32 vcc, v151, v169
	s_nop 1
	v_cndmask_b32_e32 v151, v191, v151, vcc
	v_lshlrev_b32_e32 v151, 2, v151
	ds_bpermute_b32 v151, v151, v141
	s_waitcnt lgkmcnt(0)
	v_add_f32_e32 v141, v141, v151
	v_fmamk_f32 v141, v141, 0x3a800000, v154
	v_cmp_gt_f32_e32 vcc, s84, v141
	v_mul_f32_e32 v151, 0x4b800000, v141
	s_nop 0
	v_cndmask_b32_e32 v141, v141, v151, vcc
	v_rsq_f32_e32 v141, v141
	s_nop 0
	v_mul_f32_e32 v151, 0x45800000, v141
	v_cndmask_b32_e32 v170, v141, v151, vcc
